# grid sync after prologue: L1 invalidate right after the L2 write-back instead of after the spin; stacked
# baseline (speedup 1.0000x reference)
; #define SEAM(k) do { if (lo <= (k) && (k) + 1 < hi) grid.sync(); } while (0)
; __global__ void __launch_bounds__(NTHR, 2) mk_fwd(Args a) {
;     ...
;     SEAM(0);
.LBB0_40:
	s_load_dwordx4 s[12:15], s[0:1], 0xa8
	s_waitcnt lgkmcnt(0)
	s_cmp_gt_i32 s13, 1
	s_cselect_b64 s[4:5], -1, 0
	s_and_b64 s[4:5], s[8:9], s[4:5]
	s_andn2_b64 vcc, exec, s[4:5]
	s_cbranch_vccnz .LBB0_52
	v_lshrrev_b32_e32 v1, 20, v0
	v_lshrrev_b32_e32 v0, 10, v0
	v_or_b32_e32 v0, v0, v1
	s_movk_i32 s4, 0x3ff
	v_and_or_b32 v0, v0, s4, v212
	v_cmp_eq_u32_e32 vcc, 0, v0
	s_barrier
	s_and_saveexec_b64 s[4:5], vcc
	s_cbranch_execz .LBB0_51
	buffer_wbl2 sc1
	s_waitcnt vmcnt(0)
	buffer_inv sc1
	s_load_dwordx2 s[6:7], s[6:7], 0x58
	v_mov_b32_e32 v2, 0
	s_mov_b64 s[8:9], exec
	v_mbcnt_lo_u32_b32 v1, s8, 0
	v_mbcnt_hi_u32_b32 v1, s9, v1
	s_waitcnt lgkmcnt(0)
	global_load_dword v0, v2, s[6:7] offset:40
	v_cmp_eq_u32_e32 vcc, 0, v1
	s_and_saveexec_b64 s[10:11], vcc
	s_cbranch_execz .LBB0_44
	s_bcnt1_i32_b64 s8, s[8:9]
	v_mov_b32_e32 v3, s8
	global_atomic_add v3, v2, v3, s[6:7] offset:32 sc0

; #define SEAM(k) do { if (lo <= (k) && (k) + 1 < hi) grid.sync(); } while (0)
; __global__ void __launch_bounds__(NTHR, 2) mk_fwd(Args a) {
;     ...
;     SEAM(0);
.LBB0_50:
.LBB0_51:
	s_or_b64 exec, exec, s[4:5]
	s_barrier
